# adds attention K/V staging as one burst of eight loads behind counted waits, and convert_p loads issued at phase start (on top of the barrier-poll change)
# baseline (speedup 1.0000x reference)
; #define LAS __attribute__((address_space(3)))
; __device__ __forceinline__ void attn_item(int item, const float* const* in, int l, unsigned char* ws, bf16_t* ybuf, LAS unsigned char* lds, int tid, int lane, int wave) {
;     ...
;     for (int qg = 0; qg < 4; ++qg) { const bf16_t* qp = U + ((size_t)b * SEQ + nb * 128 + qhalf * 64 + qg * 16 + fr) * NIN + U_AQ + hq * 64 + 8 * q; Bq[qg][0] = *(const bf16x8*)qp; Bq[qg][1] = *(const bf16x8*)(qp + 32); }
;     __syncthreads();
; #pragma unroll
;     for (int i = 0; i < 4; ++i) { const int key = tid & 255, part = (tid >> 8) + 2 * i, pos = (nb - 1) * 128 + key;
;         u32x4v kv = (u32x4v){0u, 0u, 0u, 0u}, vv = (u32x4v){0u, 0u, 0u, 0u};
;         if (pos >= 0) { const bf16_t* src = U + ((size_t)b * SEQ + pos) * NIN; kv = *(const u32x4v*)(src + 1024 + kh * 64 + part * 8); vv = *(const u32x4v*)(src + 1152 + kh * 64 + part * 8); }
;         *(LAS u32x4v*)(KL + key * 72 + part * 8) = kv;
;         LAS bf16_t* vd = VT + (part * 8) * 272 + key;
;         vd[0] = (bf16_t)(vv.x & 0xffffu); vd[272] = (bf16_t)(vv.x >> 16); vd[2 * 272] = (bf16_t)(vv.y & 0xffffu); vd[3 * 272] = (bf16_t)(vv.y >> 16);
;         vd[4 * 272] = (bf16_t)(vv.z & 0xffffu); vd[5 * 272] = (bf16_t)(vv.z >> 16); vd[6 * 272] = (bf16_t)(vv.w & 0xffffu); vd[7 * 272] = (bf16_t)(vv.w >> 16); }
.LBB0_840:
	s_sub_i32 s0, 0x1ff, s38
	v_mov_b32_e32 v52, v166
	s_bfe_u32 s7, s0, 0x40001
	v_readfirstlane_b32 s1, v52
	s_lshr_b32 s82, s0, 5
	s_and_b32 s18, s0, 1
	s_ashr_i32 s8, s1, 7
	s_bfe_u32 s1, s1, 0x10006
	v_and_b32_e32 v79, 15, v52
	s_lshl_b64 s[12:13], s[82:83], 11
	s_lshl_b32 s19, s7, 7
	v_readlane_b32 s14, v251, 4
	s_lshl_b32 s9, s18, 2
	s_or_b32 s0, s12, s19
	v_lshl_or_b32 v75, s1, 6, v79
	v_readlane_b32 s15, v251, 5
	s_add_i32 s6, s8, s9
	v_or_b32_e32 v70, s0, v75
	v_mov_b64_e32 v[32:33], s[14:15]
	s_lshl_b32 s10, s6, 6
	v_mad_u64_u32 v[2:3], s[14:15], v70, s36, v[32:33]
	v_bfe_u32 v78, v52, 4, 2
	s_ashr_i32 s11, s10, 31
	v_mad_u32_u24 v3, s13, v235, v3
	v_lshl_add_u64 v[2:3], s[10:11], 1, v[2:3]
	v_lshlrev_b32_e32 v0, 4, v78
	v_lshl_add_u64 v[2:3], v[2:3], 0, v[0:1]
	s_mov_b64 s[14:15], 0x14400
	v_lshl_add_u64 v[4:5], v[2:3], 0, s[14:15]
	s_mov_b32 s14, 0x14000
	v_add_co_u32_e32 v6, vcc, s14, v2
	s_mov_b64 s[14:15], 0x28400
	s_nop 0
	v_addc_co_u32_e32 v7, vcc, 0, v3, vcc
	global_load_dwordx4 v[38:41], v[2:3], off offset:1024
	global_load_dwordx4 v[26:29], v[2:3], off offset:1088
	global_load_dwordx4 v[22:25], v[6:7], off offset:1024
	global_load_dwordx4 v[18:21], v[4:5], off offset:64
	v_lshl_add_u64 v[4:5], v[2:3], 0, s[14:15]
	s_mov_b32 s14, 0x28000
	v_add_co_u32_e32 v6, vcc, s14, v2
	s_mov_b64 s[14:15], 0x3c400
	s_nop 0
	v_addc_co_u32_e32 v7, vcc, 0, v3, vcc
	global_load_dwordx4 v[14:17], v[6:7], off offset:1024
	global_load_dwordx4 v[10:13], v[4:5], off offset:64
	v_lshl_add_u64 v[4:5], v[2:3], 0, s[14:15]
	s_mov_b32 s14, 0x3c000
	v_add_co_u32_e32 v2, vcc, s14, v2
	v_and_b32_e32 v31, 0xff, v52
	s_nop 0
	v_addc_co_u32_e32 v3, vcc, 0, v3, vcc
	global_load_dwordx4 v[6:9], v[2:3], off offset:1024
	s_nop 0
	global_load_dwordx4 v[2:5], v[4:5], off offset:64
	s_addk_i32 s19, 0xff80
	v_add_u32_e32 v0, s19, v31
	v_lshl_add_u64 v[34:35], s[12:13], 0, v[0:1]
	v_mad_u64_u32 v[32:33], s[14:15], v34, s36, v[32:33]
	v_mad_u32_u24 v33, v35, s36, v33
	s_lshl_b32 s82, s18, 7
	v_mov_b32_e32 v71, s13
	v_ashrrev_i32_e32 v53, 8, v52
	v_cmp_lt_i32_e32 vcc, -1, v0
	v_lshl_add_u64 v[50:51], v[32:33], 0, s[82:83]
	v_mov_b32_e32 v34, 0
	v_mov_b32_e32 v30, 0
	v_mov_b32_e32 v42, 0
	v_mov_b32_e32 v43, 0
	v_mov_b32_e32 v44, 0
	v_mov_b32_e32 v45, 0
	v_mov_b32_e32 v46, 0
	v_mov_b32_e32 v47, 0
	v_mov_b32_e32 v48, 0
	v_mov_b32_e32 v49, 0
	s_waitcnt vmcnt(63) expcnt(7) lgkmcnt(15)
	s_barrier
	v_mad_u32_u24 v0, v31, s39, 0
	s_movk_i32 s12, 0xff72
	v_mad_i32_i24 v54, v31, s12, v0
	v_lshl_add_u32 v0, v53, 4, v0
	s_movk_i32 s12, 0x1100
	v_mad_i32_i24 v54, v53, s12, v54
	v_mov_b32_e32 v31, 0
	v_mov_b32_e32 v32, 0
	v_mov_b32_e32 v33, 0
	v_mov_b32_e32 v35, 0
	v_mov_b32_e32 v36, 0
	v_mov_b32_e32 v37, 0
	v_mov_b32_e32 v210, 0
	v_mov_b32_e32 v211, 0
	v_mov_b32_e32 v212, 0
	v_mov_b32_e32 v213, 0
	v_mov_b32_e32 v214, 0
	v_mov_b32_e32 v215, 0
	v_mov_b32_e32 v216, 0
	v_mov_b32_e32 v217, 0
	v_mov_b32_e32 v218, 0
	v_mov_b32_e32 v219, 0
	v_mov_b32_e32 v220, 0
	v_mov_b32_e32 v221, 0
	v_mov_b32_e32 v222, 0
	v_mov_b32_e32 v223, 0
	v_mov_b32_e32 v224, 0
	v_mov_b32_e32 v225, 0
	s_and_saveexec_b64 s[14:15], vcc
	s_cbranch_execz .La_ldskip
	v_lshlrev_b32_e32 v32, 3, v53
	v_ashrrev_i32_e32 v33, 31, v32
	v_lshl_add_u64 v[32:33], v[32:33], 1, v[50:51]
	global_load_dwordx4 v[46:49], v[32:33], off offset:2048
	global_load_dwordx4 v[42:45], v[32:33], off offset:2304
	global_load_dwordx4 v[34:37], v[32:33], off offset:2080
	global_load_dwordx4 v[210:213], v[32:33], off offset:2112
	global_load_dwordx4 v[218:221], v[32:33], off offset:2144
	global_load_dwordx4 v[214:217], v[32:33], off offset:2368
	global_load_dwordx4 v[222:225], v[32:33], off offset:2400
	s_nop 0
	global_load_dwordx4 v[30:33], v[32:33], off offset:2336
.La_ldskip:
	s_or_b64 exec, exec, s[14:15]
	v_add_u32_e32 v53, 0x2200, v54
	v_cmp_gt_i32_e32 vcc, s40, v52
	s_waitcnt vmcnt(7)
	ds_write_b128 v0, v[46:49]
	s_waitcnt vmcnt(6)
	ds_write_b16 v54, v42 offset:36864
	ds_write_b16_d16_hi v54, v42 offset:37408
	ds_write_b16 v54, v43 offset:37952
	ds_write_b16_d16_hi v54, v43 offset:38496
	ds_write_b16 v54, v44 offset:39040
	ds_write_b16_d16_hi v54, v44 offset:39584
	ds_write_b16 v54, v45 offset:40128
	ds_write_b16_d16_hi v54, v45 offset:40672
	s_waitcnt vmcnt(5)
	ds_write_b128 v0, v[34:37] offset:32
	s_waitcnt vmcnt(4)
	ds_write_b128 v0, v[210:213] offset:64
	s_waitcnt vmcnt(3)
	ds_write_b128 v0, v[218:221] offset:96
	s_waitcnt vmcnt(2)
	ds_write_b16 v53, v214 offset:45568
	ds_write_b16_d16_hi v53, v214 offset:46112
	ds_write_b16 v53, v215 offset:46656
	ds_write_b16_d16_hi v53, v215 offset:47200
	ds_write_b16 v53, v216 offset:47744
	ds_write_b16_d16_hi v53, v216 offset:48288
	ds_write_b16 v53, v217 offset:48832
	ds_write_b16_d16_hi v53, v217 offset:49376
	s_waitcnt vmcnt(1)
	ds_write_b16 v53, v222 offset:54272
	ds_write_b16_d16_hi v53, v222 offset:54816
	ds_write_b16 v53, v223 offset:55360
	ds_write_b16_d16_hi v53, v223 offset:55904
	ds_write_b16 v53, v224 offset:56448
	ds_write_b16_d16_hi v53, v224 offset:56992
	ds_write_b16 v53, v225 offset:57536
	ds_write_b16_d16_hi v53, v225 offset:58080
	s_waitcnt vmcnt(0)
	ds_write_b16 v53, v30 offset:36864
	ds_write_b16_d16_hi v53, v30 offset:37408
	ds_write_b16 v53, v31 offset:37952
	ds_write_b16_d16_hi v53, v31 offset:38496
	ds_write_b16 v53, v32 offset:39040
	ds_write_b16_d16_hi v53, v32 offset:39584
	ds_write_b16 v53, v33 offset:40128
	ds_write_b16_d16_hi v53, v33 offset:40672
	s_and_saveexec_b64 s[14:15], vcc
	s_cbranch_execz .LBB0_839
	s_add_i32 s12, 0, 0x12000
	v_lshl_add_u32 v0, v52, 2, s12
	s_mov_b64 s[18:19], 0
	v_mov_b32_e32 v30, v52
	s_branch .LBB0_851
